# v11 + in-proj (EpiZ) GEMM epilogue: bf16 Z stores coalesced through the same per-wave LDS transpose for the 10 of 12 column tiles that hold no gate columns (tiles 7 and 11 keep the original path); sam
# speedup vs baseline: 1.0248x; 1.0202x over previous
; DI unsigned pk2(float lo, float hi) { f32x2 v = {lo, hi}; bf2_t r = __builtin_convertvector(v, bf2_t); return __builtin_bit_cast(unsigned, r); }
;     DI void operator()(const f32x4 (&acc)[2][2][4][2], const Unit& u, int wr, int wc, int fr, int fq) const {
;         const int row0 = u.pm * BM + wr * 64 + fr, col0 = u.pn * BM + wc * 32 + 8 * fq;
; #pragma unroll
;         for (int ai = 0; ai < 2; ++ai)
; #pragma unroll
;             for (int m = 0; m < 4; ++m) { const size_t row = (size_t)(row0 + ai * HALF + m * 16);
; #pragma unroll
;                 for (int bj = 0; bj < 2; ++bj) { const int col = col0 + bj * HALF; const f32x4 v0 = acc[ai][bj][m][0], v1 = acc[ai][bj][m][1];
;                     u32x4 w; w.x = pk2(v0[0], v0[1]); w.y = pk2(v0[2], v0[3]); w.z = pk2(v1[0], v1[1]); w.w = pk2(v1[2], v1[3]);
;                     *(u32x4*)(Z + row * ZW + col) = w;
;                     int gc = -1; if (col >= C_GC && col < C_GC + 32) gc = col - C_GC; else if (col >= C_ID && col < C_ID + 16) gc = 32 + col - C_ID;
;                     if (gc >= 0) { float* gp = GATE + row * 48 + gc; *(f32x4*)gp = v0; *(f32x4*)(gp + 4) = v1; } } }
.LBB0_158:
	s_cmp_eq_u32 s25, 7
	s_cbranch_scc1 .Lepi_ip_orig
	s_cmp_eq_u32 s25, 11
	s_cbranch_scc1 .Lepi_ip_orig
	v_mbcnt_lo_u32_b32 v156, -1, 0
	v_mbcnt_hi_u32_b32 v156, -1, v156
	v_readlane_b32 s74, v253, 14
	v_readlane_b32 s76, v253, 12
	v_readlane_b32 s77, v253, 13
	v_and_b32_e32 v157, 15, v156
	v_lshrrev_b32_e32 v158, 4, v156
	v_bfe_u32 v159, v156, 2, 2
	v_xor_b32_e32 v159, v159, v158
	v_lshlrev_b32_e32 v159, 4, v159
	v_lshl_or_b32 v157, v157, 6, v159
	v_and_b32_e32 v159, 3, v156
	v_xor_b32_e32 v158, v158, v159
	v_lshlrev_b32_e32 v158, 4, v158
	v_lshrrev_b32_e32 v156, 2, v156
	v_lshl_or_b32 v158, v156, 6, v158
	s_add_i32 s75, s74, 0xc000
	v_add_u32_e32 v157, s75, v157
	v_add_u32_e32 v158, s75, v158
	v_lshlrev_b32_e32 v159, 4, v159
	v_mov_b32_e32 v160, 0x1800
	v_mad_u32_u24 v159, v156, v160, v159
	s_lshr_b32 s74, s74, 10
	s_lshr_b32 s75, s74, 2
	s_and_b32 s74, s74, 3
	s_mul_i32 s75, s75, 0x60000
	s_lshl_b32 s74, s74, 6
	s_add_i32 s75, s75, s74
	v_add_u32_e32 v159, s75, v159
	s_mul_i32 s75, s26, 0x180000
	s_lshl_b32 s74, s25, 9
	s_add_u32 s75, s75, s74
	s_add_u32 s76, s76, s75
	s_addc_u32 s77, s77, 0
	v_cvt_pk_bf16_f32 v160, v126, v127
	v_cvt_pk_bf16_f32 v161, v128, v129
	v_cvt_pk_bf16_f32 v162, v122, v123
	v_cvt_pk_bf16_f32 v163, v124, v125
	ds_write_b128 v157, v[160:163]
	ds_read_b128 v[168:171], v158
	v_cvt_pk_bf16_f32 v164, v118, v119
	v_cvt_pk_bf16_f32 v165, v120, v121
	v_cvt_pk_bf16_f32 v166, v114, v115
	v_cvt_pk_bf16_f32 v167, v116, v117
	ds_write_b128 v157, v[164:167] offset:8192
	ds_read_b128 v[172:175], v158 offset:8192
	s_waitcnt lgkmcnt(2)
	global_store_dwordx4 v159, v[168:171], s[76:77]
	v_cvt_pk_bf16_f32 v160, v108, v109
	v_cvt_pk_bf16_f32 v161, v110, v111
	v_cvt_pk_bf16_f32 v162, v104, v105
	v_cvt_pk_bf16_f32 v163, v106, v107
	ds_write_b128 v157, v[160:163]
	ds_read_b128 v[176:179], v158
	s_waitcnt lgkmcnt(2)
	global_store_dwordx4 v159, v[172:175], s[76:77] offset:256
	v_cvt_pk_bf16_f32 v164, v100, v101
	v_cvt_pk_bf16_f32 v165, v102, v103
	v_cvt_pk_bf16_f32 v166, v96, v97
	v_cvt_pk_bf16_f32 v167, v98, v99
	ds_write_b128 v157, v[164:167] offset:8192
	ds_read_b128 v[180:183], v158 offset:8192
	s_waitcnt lgkmcnt(2)
	s_add_u32 s76, s76, 0x18000
	s_addc_u32 s77, s77, 0
	global_store_dwordx4 v159, v[176:179], s[76:77]
	v_cvt_pk_bf16_f32 v160, v92, v93
	v_cvt_pk_bf16_f32 v161, v94, v95
	v_cvt_pk_bf16_f32 v162, v88, v89
	v_cvt_pk_bf16_f32 v163, v90, v91
	ds_write_b128 v157, v[160:163]
	ds_read_b128 v[168:171], v158
	s_waitcnt lgkmcnt(2)
	global_store_dwordx4 v159, v[180:183], s[76:77] offset:256
	v_cvt_pk_bf16_f32 v164, v84, v85
	v_cvt_pk_bf16_f32 v165, v86, v87
	v_cvt_pk_bf16_f32 v166, v80, v81
	v_cvt_pk_bf16_f32 v167, v82, v83
	ds_write_b128 v157, v[164:167] offset:8192
	ds_read_b128 v[172:175], v158 offset:8192
	s_waitcnt lgkmcnt(2)
	s_add_u32 s76, s76, 0x18000
	s_addc_u32 s77, s77, 0
	global_store_dwordx4 v159, v[168:171], s[76:77]
	v_cvt_pk_bf16_f32 v160, v76, v77
	v_cvt_pk_bf16_f32 v161, v78, v79
	v_cvt_pk_bf16_f32 v162, v72, v73
	v_cvt_pk_bf16_f32 v163, v74, v75
	ds_write_b128 v157, v[160:163]
	ds_read_b128 v[176:179], v158
	s_waitcnt lgkmcnt(2)
	global_store_dwordx4 v159, v[172:175], s[76:77] offset:256
	v_cvt_pk_bf16_f32 v164, v68, v69
	v_cvt_pk_bf16_f32 v165, v70, v71
	v_cvt_pk_bf16_f32 v166, v64, v65
	v_cvt_pk_bf16_f32 v167, v66, v67
	ds_write_b128 v157, v[164:167] offset:8192
	ds_read_b128 v[180:183], v158 offset:8192
	s_waitcnt lgkmcnt(2)
	s_add_u32 s76, s76, 0x18000
	s_addc_u32 s77, s77, 0
	global_store_dwordx4 v159, v[176:179], s[76:77]
	v_cvt_pk_bf16_f32 v160, v60, v61
	v_cvt_pk_bf16_f32 v161, v62, v63
	v_cvt_pk_bf16_f32 v162, v56, v57
	v_cvt_pk_bf16_f32 v163, v58, v59
	ds_write_b128 v157, v[160:163]
	ds_read_b128 v[168:171], v158
	s_waitcnt lgkmcnt(2)
	global_store_dwordx4 v159, v[180:183], s[76:77] offset:256
	v_cvt_pk_bf16_f32 v164, v52, v53
	v_cvt_pk_bf16_f32 v165, v54, v55
	v_cvt_pk_bf16_f32 v166, v48, v49
	v_cvt_pk_bf16_f32 v167, v50, v51
	ds_write_b128 v157, v[164:167] offset:8192
	ds_read_b128 v[172:175], v158 offset:8192
	s_waitcnt lgkmcnt(2)
	s_add_u32 s76, s76, 0x78000
	s_addc_u32 s77, s77, 0
	global_store_dwordx4 v159, v[168:171], s[76:77]
	v_cvt_pk_bf16_f32 v160, v44, v45
	v_cvt_pk_bf16_f32 v161, v46, v47
	v_cvt_pk_bf16_f32 v162, v40, v41
	v_cvt_pk_bf16_f32 v163, v42, v43
	ds_write_b128 v157, v[160:163]
	ds_read_b128 v[176:179], v158
	s_waitcnt lgkmcnt(2)
	global_store_dwordx4 v159, v[172:175], s[76:77] offset:256
	v_cvt_pk_bf16_f32 v164, v36, v37
	v_cvt_pk_bf16_f32 v165, v38, v39
	v_cvt_pk_bf16_f32 v166, v32, v33
	v_cvt_pk_bf16_f32 v167, v34, v35
	ds_write_b128 v157, v[164:167] offset:8192
	ds_read_b128 v[180:183], v158 offset:8192
	s_waitcnt lgkmcnt(2)
	s_add_u32 s76, s76, 0x18000
	s_addc_u32 s77, s77, 0
	global_store_dwordx4 v159, v[176:179], s[76:77]
	v_cvt_pk_bf16_f32 v160, v28, v29
	v_cvt_pk_bf16_f32 v161, v30, v31
	v_cvt_pk_bf16_f32 v162, v24, v25
	v_cvt_pk_bf16_f32 v163, v26, v27
	ds_write_b128 v157, v[160:163]
	ds_read_b128 v[168:171], v158
	s_waitcnt lgkmcnt(2)
	global_store_dwordx4 v159, v[180:183], s[76:77] offset:256
	v_cvt_pk_bf16_f32 v164, v20, v21
	v_cvt_pk_bf16_f32 v165, v22, v23
	v_cvt_pk_bf16_f32 v166, v16, v17
	v_cvt_pk_bf16_f32 v167, v18, v19
	ds_write_b128 v157, v[164:167] offset:8192
	ds_read_b128 v[172:175], v158 offset:8192
	s_waitcnt lgkmcnt(2)
	s_add_u32 s76, s76, 0x18000
	s_addc_u32 s77, s77, 0
	global_store_dwordx4 v159, v[168:171], s[76:77]
	v_cvt_pk_bf16_f32 v160, v12, v13
	v_cvt_pk_bf16_f32 v161, v14, v15
	v_cvt_pk_bf16_f32 v162, v8, v9
	v_cvt_pk_bf16_f32 v163, v10, v11
	ds_write_b128 v157, v[160:163]
	ds_read_b128 v[176:179], v158
	s_waitcnt lgkmcnt(2)
	global_store_dwordx4 v159, v[172:175], s[76:77] offset:256
	v_cvt_pk_bf16_f32 v164, v4, v5
	v_cvt_pk_bf16_f32 v165, v6, v7
	v_cvt_pk_bf16_f32 v166, v0, v1
	v_cvt_pk_bf16_f32 v167, v2, v3
	ds_write_b128 v157, v[164:167] offset:8192
	ds_read_b128 v[180:183], v158 offset:8192
	s_waitcnt lgkmcnt(2)
	s_add_u32 s76, s76, 0x18000
	s_addc_u32 s77, s77, 0
	global_store_dwordx4 v159, v[176:179], s[76:77]
	s_waitcnt lgkmcnt(0)
	global_store_dwordx4 v159, v[180:183], s[76:77] offset:256
	s_movk_i32 s36, 0x44
	s_andn2_b64 vcc, exec, s[0:1]
	s_mov_b64 s[0:1], -1
	s_cbranch_vccnz .LBB0_151
	s_branch .Lepi_ip_after
	s_nop 0

; #define PG8_BAR __builtin_amdgcn_s_barrier()
; template <class Epi>
; DI void gemm_phase(LAS unsigned char* lds, const Gemm g, const Order& S, const Epi& E, const int wv) {
;     ...
;         cur = nxt; cA = nA; cB = nB; ++ui;
;         if (wr == 1) PG8_BAR;
;     }
.Lepi_ip_after:
	v_readlane_b32 s0, v254, 58
	v_readlane_b32 s1, v254, 59
	s_and_b64 vcc, exec, s[0:1]
	s_cbranch_vccnz .LBB0_150
	s_barrier
	s_branch .LBB0_150
